# EpiC: the two 8-byte ACT stores of each token row (column groups n=0/n=1) paired into one 16-byte store; 8 address mads removed
# baseline (speedup 1.0000x reference)
; #define LAS __attribute__((address_space(3)))
;     __device__ __forceinline__ void operator()(const f32x4 (&acc)[2][2][4][2], const CU2& u, int wr, int wc, int fr_, int fq_) const {
;     ...
;         for (int n = 0; n < 2; ++n) {
;             const float* wp = cw + 128 * u.pn + cl + 4 * n; const float* bp = cb + 128 * u.pn + cl + 4 * n;
;             const f32x4 g0 = *(const f32x4*)wp, g1 = *(const f32x4*)(wp + 2 * FF_), g2 = *(const f32x4*)(wp + 4 * FF_), gb = *(const f32x4*)bp;
;             const f32x4 v0 = *(const f32x4*)(wp + FF_), v1 = *(const f32x4*)(wp + 3 * FF_), v2 = *(const f32x4*)(wp + 5 * FF_), vb = *(const f32x4*)(bp + FF_);
;             f32x4 pg2 = acc[1][0][2][n] * rsv[6], pg1 = acc[1][0][3][n] * rsv[7], pv2 = acc[1][1][2][n] * rsv[6], pv1 = acc[1][1][3][n] * rsv[7];
; #pragma unroll
;             for (int e = 0; e < 4; ++e) {
;                 pg2[e] = __int_as_float(__builtin_amdgcn_mov_dpp(__float_as_int(pg2[e]), 0x111, 0xF, 0xF, true)); pg1[e] = __int_as_float(__builtin_amdgcn_mov_dpp(__float_as_int(pg1[e]), 0x111, 0xF, 0xF, true));
;                 pv2[e] = __int_as_float(__builtin_amdgcn_mov_dpp(__float_as_int(pv2[e]), 0x111, 0xF, 0xF, true)); pv1[e] = __int_as_float(__builtin_amdgcn_mov_dpp(__float_as_int(pv1[e]), 0x111, 0xF, 0xF, true));
;             }
;             if (fr == 0 && wr == 1) { pg2 = *(const LAS f32x4*)(hal + cl + 4 * n); pg1 = *(const LAS f32x4*)(hal + 256 + cl + 4 * n); pv2 = *(const LAS f32x4*)(hal + 128 + cl + 4 * n); pv1 = *(const LAS f32x4*)(hal + 384 + cl + 4 * n); }
; #pragma unroll
;             for (int j = 0; j < 8; ++j) {
;                 const f32x4 xg = acc[j >> 2][0][j & 3][n] * rsv[j], xv = acc[j >> 2][1][j & 3][n] * rsv[j];
;                 const f32x4 gc = gb + g2 * xg + g1 * pg1 + g0 * pg2, vc = vb + v2 * xv + v1 * pv1 + v0 * pv2;
;                 f32x4 sg;
; #pragma unroll
;                 for (int e = 0; e < 4; ++e) sg[e] = __builtin_amdgcn_rcpf(1.f + __expf(-gc[e]));
;                 const f32x4 o4 = gc * sg * vc;
;                 pg2 = pg1; pg1 = xg; pv2 = pv1; pv1 = xv;
;                 if (rb + j >= 2 && tb + j < T_) { u32x2 w; w.x = cvt_pk_bf16(o4[0], o4[1]); w.y = cvt_pk_bf16(o4[2], o4[3]); *(u32x2*)(act + (size_t)(tb + j) * FF_ + 128 * u.pn + cl + 4 * n) = w; }
.LBB0_931:
	s_or_b64 exec, exec, s[6:7]
	s_lshl_b64 s[0:1], s[0:1], 1
	s_add_u32 s0, s44, s0
	s_addc_u32 s1, s45, s1
	v_lshl_add_u64 v[50:51], v[226:227], 1, s[0:1]
	v_cmp_lt_i32_e32 vcc, 1, v225
	v_cmp_gt_i32_e64 s[0:1], s89, v200
	v_pk_mul_f32 v[80:81], v[150:151], v[228:229] op_sel_hi:[1,0]
	v_pk_mul_f32 v[68:69], v[148:149], v[228:229] op_sel_hi:[1,0]
	v_pk_mul_f32 v[130:131], v[146:147], v[228:229] op_sel_hi:[1,0]
	v_pk_mul_f32 v[134:135], v[144:145], v[228:229] op_sel_hi:[1,0]
	s_and_b64 s[10:11], vcc, s[0:1]
	s_and_saveexec_b64 s[0:1], s[10:11]
	s_cbranch_execz .LBB0_933
	s_waitcnt lgkmcnt(0)
	v_pk_fma_f32 v[84:85], v[80:81], v[166:167], v[170:171]
	v_pk_fma_f32 v[138:139], v[68:69], v[164:165], v[168:169]
	s_waitcnt lgkmcnt(2)
	v_pk_fma_f32 v[84:85], v[162:163], v[186:187], v[84:85]
	v_pk_fma_f32 v[138:139], v[160:161], v[184:185], v[138:139]
	v_pk_fma_f32 v[84:85], v[154:155], v[194:195], v[84:85]
	v_pk_fma_f32 v[138:139], v[152:153], v[192:193], v[138:139]
	v_mul_f32_e32 v146, 0xbfb8aa3b, v84
	v_mul_f32_e32 v144, 0xbfb8aa3b, v138
	v_mul_f32_e32 v145, 0xbfb8aa3b, v139
	v_mul_f32_e32 v147, 0xbfb8aa3b, v85
	v_exp_f32_e32 v144, v144
	v_exp_f32_e32 v145, v145
	v_exp_f32_e32 v146, v146
	v_exp_f32_e32 v147, v147
	v_add_f32_e32 v144, 1.0, v144
	v_add_f32_e32 v145, 1.0, v145
	v_add_f32_e32 v146, 1.0, v146
	v_add_f32_e32 v147, 1.0, v147
	v_rcp_f32_e32 v144, v144
	v_rcp_f32_e32 v145, v145
	v_rcp_f32_e32 v146, v146
	v_rcp_f32_e32 v147, v147
	s_waitcnt lgkmcnt(0)
	v_pk_fma_f32 v[72:73], v[130:131], v[178:179], v[182:183]
	v_pk_fma_f32 v[76:77], v[134:135], v[176:177], v[180:181]
	s_waitcnt lgkmcnt(0)
	v_pk_fma_f32 v[72:73], v[174:175], v[190:191], v[72:73]
	v_pk_fma_f32 v[76:77], v[172:173], v[188:189], v[76:77]
	v_pk_fma_f32 v[72:73], v[158:159], v[198:199], v[72:73]
	v_pk_fma_f32 v[76:77], v[156:157], v[196:197], v[76:77]
	v_pk_mul_f32 v[84:85], v[84:85], v[146:147]
	v_pk_mul_f32 v[138:139], v[138:139], v[144:145]
	v_pk_mul_f32 v[72:73], v[72:73], v[84:85]
	v_pk_mul_f32 v[76:77], v[76:77], v[138:139]
	s_nop 0
	v_cvt_pk_bf16_f32 v148, v76, v77
	v_cvt_pk_bf16_f32 v149, v72, v73
.LBB0_933:
	s_or_b64 exec, exec, s[0:1]
	s_movk_i32 s0, 0x1fff
	v_cmp_lt_i32_e32 vcc, 0, v225
	v_cmp_gt_i32_e64 s[0:1], s0, v200
	v_pk_mul_f32 v[126:127], v[126:127], v[224:225] op_sel_hi:[1,0]
	v_pk_mul_f32 v[76:77], v[124:125], v[224:225] op_sel_hi:[1,0]
	v_pk_mul_f32 v[122:123], v[122:123], v[224:225] op_sel_hi:[1,0]
	v_pk_mul_f32 v[120:121], v[120:121], v[224:225] op_sel_hi:[1,0]
	s_and_b64 s[6:7], vcc, s[0:1]
	s_and_saveexec_b64 s[0:1], s[6:7]
	s_cbranch_execz .LBB0_935
	v_pk_fma_f32 v[124:125], v[126:127], v[166:167], v[170:171]
	v_pk_fma_f32 v[138:139], v[76:77], v[164:165], v[168:169]
	v_pk_fma_f32 v[124:125], v[80:81], v[162:163], v[124:125]
	v_pk_fma_f32 v[138:139], v[68:69], v[160:161], v[138:139]
	s_waitcnt lgkmcnt(0)
	v_pk_fma_f32 v[124:125], v[154:155], v[186:187], v[124:125]
	v_pk_fma_f32 v[138:139], v[152:153], v[184:185], v[138:139]
	v_mul_f32_e32 v146, 0xbfb8aa3b, v124
	v_mul_f32_e32 v144, 0xbfb8aa3b, v138
	v_mul_f32_e32 v145, 0xbfb8aa3b, v139
	v_mul_f32_e32 v147, 0xbfb8aa3b, v125
	v_exp_f32_e32 v144, v144
	v_exp_f32_e32 v145, v145
	v_exp_f32_e32 v146, v146
	v_exp_f32_e32 v147, v147
	v_add_f32_e32 v144, 1.0, v144
	v_add_f32_e32 v145, 1.0, v145
	v_add_f32_e32 v146, 1.0, v146
	v_add_f32_e32 v147, 1.0, v147
	v_rcp_f32_e32 v144, v144
	v_rcp_f32_e32 v145, v145
	v_rcp_f32_e32 v146, v146
	v_rcp_f32_e32 v147, v147
	v_pk_fma_f32 v[72:73], v[122:123], v[178:179], v[182:183]
	v_pk_fma_f32 v[84:85], v[120:121], v[176:177], v[180:181]
	v_pk_fma_f32 v[72:73], v[130:131], v[174:175], v[72:73]
	v_pk_fma_f32 v[84:85], v[134:135], v[172:173], v[84:85]
	v_pk_fma_f32 v[72:73], v[158:159], v[190:191], v[72:73]
	v_pk_fma_f32 v[84:85], v[156:157], v[188:189], v[84:85]
	v_pk_mul_f32 v[124:125], v[124:125], v[146:147]
	v_pk_mul_f32 v[138:139], v[138:139], v[144:145]
	v_pk_mul_f32 v[72:73], v[72:73], v[124:125]
	v_pk_mul_f32 v[84:85], v[84:85], v[138:139]
	s_nop 0
	v_cvt_pk_bf16_f32 v144, v84, v85
	v_cvt_pk_bf16_f32 v145, v72, v73
.LBB0_935:
	s_or_b64 exec, exec, s[0:1]
	v_cmp_lt_i32_e32 vcc, -1, v225
	v_cmp_gt_i32_e64 s[0:1], s89, v221
	v_pk_mul_f32 v[84:85], v[118:119], v[222:223] op_sel_hi:[1,0]
	v_pk_mul_f32 v[72:73], v[116:117], v[222:223] op_sel_hi:[1,0]
	v_pk_mul_f32 v[114:115], v[114:115], v[222:223] op_sel_hi:[1,0]
	v_pk_mul_f32 v[112:113], v[112:113], v[222:223] op_sel_hi:[1,0]
	s_and_b64 s[8:9], vcc, s[0:1]
	s_and_saveexec_b64 s[0:1], s[8:9]
	s_cbranch_execz .LBB0_937
	v_pk_fma_f32 v[116:117], v[114:115], v[178:179], v[182:183]
	v_pk_fma_f32 v[124:125], v[84:85], v[166:167], v[170:171]
	v_pk_fma_f32 v[116:117], v[122:123], v[174:175], v[116:117]
	v_pk_fma_f32 v[124:125], v[126:127], v[162:163], v[124:125]
	v_pk_fma_f32 v[116:117], v[130:131], v[158:159], v[116:117]
	v_pk_fma_f32 v[130:131], v[72:73], v[164:165], v[168:169]
	v_pk_fma_f32 v[80:81], v[80:81], v[154:155], v[124:125]
	v_pk_fma_f32 v[130:131], v[76:77], v[160:161], v[130:131]
	v_pk_fma_f32 v[118:119], v[112:113], v[176:177], v[180:181]
	v_pk_fma_f32 v[68:69], v[68:69], v[152:153], v[130:131]
	v_mul_f32_e32 v130, 0xbfb8aa3b, v80
	v_mul_f32_e32 v124, 0xbfb8aa3b, v68
	v_mul_f32_e32 v125, 0xbfb8aa3b, v69
	v_mul_f32_e32 v131, 0xbfb8aa3b, v81
	v_exp_f32_e32 v124, v124
	v_exp_f32_e32 v125, v125
	v_exp_f32_e32 v130, v130
	v_exp_f32_e32 v131, v131
	v_add_f32_e32 v124, 1.0, v124
	v_add_f32_e32 v125, 1.0, v125
	v_add_f32_e32 v130, 1.0, v130
	v_add_f32_e32 v131, 1.0, v131
	v_rcp_f32_e32 v124, v124
	v_rcp_f32_e32 v125, v125
	v_rcp_f32_e32 v130, v130
	v_rcp_f32_e32 v131, v131
	v_pk_fma_f32 v[118:119], v[120:121], v[172:173], v[118:119]
	v_pk_mul_f32 v[68:69], v[68:69], v[124:125]
	v_pk_fma_f32 v[118:119], v[134:135], v[156:157], v[118:119]
	v_pk_mul_f32 v[80:81], v[80:81], v[130:131]
	v_pk_mul_f32 v[68:69], v[118:119], v[68:69]
	v_pk_mul_f32 v[80:81], v[116:117], v[80:81]
	v_cvt_pk_bf16_f32 v184, v68, v69
	s_nop 0
	v_cvt_pk_bf16_f32 v185, v80, v81
; __device__ __forceinline__ unsigned cvt_pk_bf16(float lo, float hi) { unsigned r; asm("v_cvt_pk_bf16_f32 %0, %1, %2" : "=v"(r) : "v"(lo), "v"(hi)); return r; }
;     __device__ __forceinline__ void operator()(const f32x4 (&acc)[2][2][4][2], const CU2& u, int wr, int wc, int fr_, int fq_) const {
;     ...
;             for (int j = 0; j < 8; ++j) {
;                 const f32x4 xg = acc[j >> 2][0][j & 3][n] * rsv[j], xv = acc[j >> 2][1][j & 3][n] * rsv[j];
;                 const f32x4 gc = gb + g2 * xg + g1 * pg1 + g0 * pg2, vc = vb + v2 * xv + v1 * pv1 + v0 * pv2;
;                 f32x4 sg;
; #pragma unroll
;                 for (int e = 0; e < 4; ++e) sg[e] = __builtin_amdgcn_rcpf(1.f + __expf(-gc[e]));
;                 const f32x4 o4 = gc * sg * vc;
;                 pg2 = pg1; pg1 = xg; pv2 = pv1; pv1 = xv;
;                 if (rb + j >= 2 && tb + j < T_) { u32x2 w; w.x = cvt_pk_bf16(o4[0], o4[1]); w.y = cvt_pk_bf16(o4[2], o4[3]); *(u32x2*)(act + (size_t)(tb + j) * FF_ + 128 * u.pn + cl + 4 * n) = w; }
.LBB0_937:
	s_or_b64 exec, exec, s[0:1]
	s_movk_i32 s0, 0x1ffd
	v_cmp_lt_i32_e32 vcc, -2, v225
	v_cmp_gt_i32_e64 s[0:1], s0, v200
	v_pk_mul_f32 v[80:81], v[110:111], v[220:221] op_sel_hi:[1,0]
	v_pk_mul_f32 v[68:69], v[108:109], v[220:221] op_sel_hi:[1,0]
	v_pk_mul_f32 v[106:107], v[106:107], v[220:221] op_sel_hi:[1,0]
	v_pk_mul_f32 v[104:105], v[104:105], v[220:221] op_sel_hi:[1,0]
	s_and_b64 s[12:13], vcc, s[0:1]
	s_and_saveexec_b64 s[0:1], s[12:13]
	s_cbranch_execz .LBB0_939
	v_pk_fma_f32 v[116:117], v[80:81], v[166:167], v[170:171]
	v_pk_fma_f32 v[118:119], v[68:69], v[164:165], v[168:169]
	v_pk_fma_f32 v[110:111], v[104:105], v[176:177], v[180:181]
	v_pk_fma_f32 v[116:117], v[84:85], v[162:163], v[116:117]
	v_pk_fma_f32 v[118:119], v[72:73], v[160:161], v[118:119]
	v_pk_fma_f32 v[110:111], v[112:113], v[172:173], v[110:111]
	v_pk_fma_f32 v[116:117], v[126:127], v[154:155], v[116:117]
	v_pk_fma_f32 v[76:77], v[76:77], v[152:153], v[118:119]
	v_pk_fma_f32 v[110:111], v[120:121], v[156:157], v[110:111]
	v_mul_f32_e32 v118, 0xbfb8aa3b, v76
	v_mul_f32_e32 v119, 0xbfb8aa3b, v77
	v_mul_f32_e32 v120, 0xbfb8aa3b, v116
	v_mul_f32_e32 v121, 0xbfb8aa3b, v117
	v_exp_f32_e32 v118, v118
	v_exp_f32_e32 v119, v119
	v_exp_f32_e32 v120, v120
	v_exp_f32_e32 v121, v121
	v_add_f32_e32 v118, 1.0, v118
	v_add_f32_e32 v119, 1.0, v119
	v_add_f32_e32 v120, 1.0, v120
	v_add_f32_e32 v121, 1.0, v121
	v_rcp_f32_e32 v118, v118
	v_rcp_f32_e32 v119, v119
	v_rcp_f32_e32 v120, v120
	v_rcp_f32_e32 v121, v121
	v_pk_fma_f32 v[108:109], v[106:107], v[178:179], v[182:183]
	v_pk_mul_f32 v[76:77], v[76:77], v[118:119]
	v_pk_fma_f32 v[108:109], v[114:115], v[174:175], v[108:109]
	v_pk_mul_f32 v[116:117], v[116:117], v[120:121]
	v_pk_fma_f32 v[108:109], v[122:123], v[158:159], v[108:109]
	v_pk_mul_f32 v[76:77], v[110:111], v[76:77]
	v_pk_mul_f32 v[108:109], v[108:109], v[116:117]
	v_cvt_pk_bf16_f32 v188, v76, v77
	s_nop 0
	v_cvt_pk_bf16_f32 v189, v108, v109
.LBB0_939:
	s_or_b64 exec, exec, s[0:1]
	s_movk_i32 s0, 0x1ffc
	v_cmp_lt_i32_e32 vcc, -3, v225
	v_cmp_gt_i32_e64 s[0:1], s0, v200
	v_pk_mul_f32 v[102:103], v[102:103], v[218:219] op_sel_hi:[1,0]
	v_pk_mul_f32 v[76:77], v[100:101], v[218:219] op_sel_hi:[1,0]
	v_pk_mul_f32 v[98:99], v[98:99], v[218:219] op_sel_hi:[1,0]
	v_pk_mul_f32 v[96:97], v[96:97], v[218:219] op_sel_hi:[1,0]
	s_and_b64 s[14:15], vcc, s[0:1]
	s_and_saveexec_b64 s[0:1], s[14:15]
	s_cbranch_execz .LBB0_941
	v_pk_fma_f32 v[108:109], v[96:97], v[176:177], v[180:181]
	v_pk_fma_f32 v[110:111], v[102:103], v[166:167], v[170:171]
	v_pk_fma_f32 v[108:109], v[104:105], v[172:173], v[108:109]
	v_pk_fma_f32 v[110:111], v[80:81], v[162:163], v[110:111]
	v_pk_fma_f32 v[108:109], v[112:113], v[156:157], v[108:109]
	v_pk_fma_f32 v[112:113], v[76:77], v[164:165], v[168:169]
	v_pk_fma_f32 v[84:85], v[84:85], v[154:155], v[110:111]
	v_pk_fma_f32 v[112:113], v[68:69], v[160:161], v[112:113]
	v_pk_fma_f32 v[100:101], v[98:99], v[178:179], v[182:183]
	v_pk_fma_f32 v[72:73], v[72:73], v[152:153], v[112:113]
	v_mul_f32_e32 v112, 0xbfb8aa3b, v84
	v_mul_f32_e32 v110, 0xbfb8aa3b, v72
	v_mul_f32_e32 v111, 0xbfb8aa3b, v73
	v_mul_f32_e32 v113, 0xbfb8aa3b, v85
	v_exp_f32_e32 v110, v110
	v_exp_f32_e32 v111, v111
	v_exp_f32_e32 v112, v112
	v_exp_f32_e32 v113, v113
	v_add_f32_e32 v110, 1.0, v110
	v_add_f32_e32 v111, 1.0, v111
	v_add_f32_e32 v112, 1.0, v112
	v_add_f32_e32 v113, 1.0, v113
	v_rcp_f32_e32 v110, v110
	v_rcp_f32_e32 v111, v111
	v_rcp_f32_e32 v112, v112
	v_rcp_f32_e32 v113, v113
	v_pk_fma_f32 v[100:101], v[106:107], v[174:175], v[100:101]
	v_pk_mul_f32 v[72:73], v[72:73], v[110:111]
	v_pk_fma_f32 v[100:101], v[114:115], v[158:159], v[100:101]
	v_pk_mul_f32 v[84:85], v[84:85], v[112:113]
	v_pk_mul_f32 v[72:73], v[108:109], v[72:73]
	v_pk_mul_f32 v[84:85], v[100:101], v[84:85]
	v_cvt_pk_bf16_f32 v192, v72, v73
	s_nop 0
	v_cvt_pk_bf16_f32 v193, v84, v85
; __device__ __forceinline__ unsigned cvt_pk_bf16(float lo, float hi) { unsigned r; asm("v_cvt_pk_bf16_f32 %0, %1, %2" : "=v"(r) : "v"(lo), "v"(hi)); return r; }
;     __device__ __forceinline__ void operator()(const f32x4 (&acc)[2][2][4][2], const CU2& u, int wr, int wc, int fr_, int fq_) const {
;     ...
;             for (int j = 0; j < 8; ++j) {
;                 const f32x4 xg = acc[j >> 2][0][j & 3][n] * rsv[j], xv = acc[j >> 2][1][j & 3][n] * rsv[j];
;                 const f32x4 gc = gb + g2 * xg + g1 * pg1 + g0 * pg2, vc = vb + v2 * xv + v1 * pv1 + v0 * pv2;
;                 f32x4 sg;
; #pragma unroll
;                 for (int e = 0; e < 4; ++e) sg[e] = __builtin_amdgcn_rcpf(1.f + __expf(-gc[e]));
;                 const f32x4 o4 = gc * sg * vc;
;                 pg2 = pg1; pg1 = xg; pv2 = pv1; pv1 = xv;
;                 if (rb + j >= 2 && tb + j < T_) { u32x2 w; w.x = cvt_pk_bf16(o4[0], o4[1]); w.y = cvt_pk_bf16(o4[2], o4[3]); *(u32x2*)(act + (size_t)(tb + j) * FF_ + 128 * u.pn + cl + 4 * n) = w; }
.LBB0_941:
	s_or_b64 exec, exec, s[0:1]
	s_movk_i32 s0, 0x1ffb
	v_cmp_lt_i32_e32 vcc, -4, v225
	v_cmp_gt_i32_e64 s[0:1], s0, v200
	v_pk_mul_f32 v[94:95], v[94:95], v[216:217] op_sel_hi:[1,0]
	v_pk_mul_f32 v[92:93], v[92:93], v[216:217] op_sel_hi:[1,0]
	v_pk_mul_f32 v[72:73], v[90:91], v[216:217] op_sel_hi:[1,0]
	v_pk_mul_f32 v[84:85], v[88:89], v[216:217] op_sel_hi:[1,0]
	s_and_b64 s[26:27], vcc, s[0:1]
	s_and_saveexec_b64 s[0:1], s[26:27]
	s_cbranch_execz .LBB0_943
	v_pk_fma_f32 v[90:91], v[84:85], v[176:177], v[180:181]
	v_pk_fma_f32 v[100:101], v[94:95], v[166:167], v[170:171]
	v_pk_fma_f32 v[90:91], v[96:97], v[172:173], v[90:91]
	v_pk_fma_f32 v[100:101], v[102:103], v[162:163], v[100:101]
	v_pk_fma_f32 v[90:91], v[104:105], v[156:157], v[90:91]
	v_pk_fma_f32 v[104:105], v[92:93], v[164:165], v[168:169]
	v_pk_fma_f32 v[80:81], v[80:81], v[154:155], v[100:101]
	v_pk_fma_f32 v[104:105], v[76:77], v[160:161], v[104:105]
	v_pk_fma_f32 v[88:89], v[72:73], v[178:179], v[182:183]
	v_pk_fma_f32 v[68:69], v[68:69], v[152:153], v[104:105]
	v_mul_f32_e32 v104, 0xbfb8aa3b, v80
	v_mul_f32_e32 v100, 0xbfb8aa3b, v68
	v_mul_f32_e32 v101, 0xbfb8aa3b, v69
	v_mul_f32_e32 v105, 0xbfb8aa3b, v81
	v_exp_f32_e32 v100, v100
	v_exp_f32_e32 v101, v101
	v_exp_f32_e32 v104, v104
	v_exp_f32_e32 v105, v105
	v_add_f32_e32 v100, 1.0, v100
	v_add_f32_e32 v101, 1.0, v101
	v_add_f32_e32 v104, 1.0, v104
	v_add_f32_e32 v105, 1.0, v105
	v_rcp_f32_e32 v100, v100
	v_rcp_f32_e32 v101, v101
	v_rcp_f32_e32 v104, v104
	v_rcp_f32_e32 v105, v105
	v_pk_fma_f32 v[88:89], v[98:99], v[174:175], v[88:89]
	v_pk_mul_f32 v[68:69], v[68:69], v[100:101]
	v_pk_fma_f32 v[88:89], v[106:107], v[158:159], v[88:89]
	v_pk_mul_f32 v[80:81], v[80:81], v[104:105]
	v_pk_mul_f32 v[68:69], v[90:91], v[68:69]
	v_pk_mul_f32 v[80:81], v[88:89], v[80:81]
	v_cvt_pk_bf16_f32 v196, v68, v69
	s_nop 0
	v_cvt_pk_bf16_f32 v197, v80, v81
.LBB0_943:
	s_or_b64 exec, exec, s[0:1]
	s_movk_i32 s0, 0x1ffa
	v_mov_b32_e32 v233, v232
	v_cmp_lt_i32_e32 vcc, -5, v225
	v_cmp_gt_i32_e64 s[0:1], s0, v200
	v_pk_mul_f32 v[68:69], v[86:87], v[232:233]
	s_and_b64 s[28:29], vcc, s[0:1]
	s_and_saveexec_b64 s[0:1], s[28:29]
	s_cbranch_execz .LBB0_945
	v_pk_fma_f32 v[88:89], v[142:143], v[166:167], v[170:171]
	v_pk_fma_f32 v[90:91], v[140:141], v[164:165], v[168:169]
	v_pk_fma_f32 v[86:87], v[132:133], v[176:177], v[180:181]
	v_pk_fma_f32 v[88:89], v[94:95], v[162:163], v[88:89]
	v_pk_fma_f32 v[90:91], v[92:93], v[160:161], v[90:91]
	v_pk_fma_f32 v[86:87], v[84:85], v[172:173], v[86:87]
	v_pk_fma_f32 v[88:89], v[102:103], v[154:155], v[88:89]
	v_pk_fma_f32 v[76:77], v[76:77], v[152:153], v[90:91]
	v_pk_fma_f32 v[86:87], v[96:97], v[156:157], v[86:87]
	v_mul_f32_e32 v90, 0xbfb8aa3b, v76
	v_mul_f32_e32 v91, 0xbfb8aa3b, v77
	v_mul_f32_e32 v96, 0xbfb8aa3b, v88
	v_mul_f32_e32 v97, 0xbfb8aa3b, v89
	v_exp_f32_e32 v90, v90
	v_exp_f32_e32 v91, v91
	v_exp_f32_e32 v96, v96
	v_exp_f32_e32 v97, v97
	v_add_f32_e32 v90, 1.0, v90
	v_add_f32_e32 v91, 1.0, v91
	v_add_f32_e32 v96, 1.0, v96
	v_add_f32_e32 v97, 1.0, v97
	v_rcp_f32_e32 v90, v90
	v_rcp_f32_e32 v91, v91
	v_rcp_f32_e32 v96, v96
	v_rcp_f32_e32 v97, v97
	v_pk_fma_f32 v[80:81], v[68:69], v[178:179], v[182:183]
	v_pk_mul_f32 v[76:77], v[76:77], v[90:91]
	v_pk_fma_f32 v[80:81], v[72:73], v[174:175], v[80:81]
	v_pk_mul_f32 v[88:89], v[88:89], v[96:97]
	v_pk_fma_f32 v[80:81], v[98:99], v[158:159], v[80:81]
	v_pk_mul_f32 v[76:77], v[86:87], v[76:77]
	v_pk_mul_f32 v[80:81], v[80:81], v[88:89]
	v_cvt_pk_bf16_f32 v248, v76, v77
	s_nop 0
	v_cvt_pk_bf16_f32 v249, v80, v81
.LBB0_945:
	s_or_b64 exec, exec, s[0:1]
	s_movk_i32 s0, 0x1ff9
	v_cmp_lt_i32_e32 vcc, -6, v225
	v_cmp_gt_i32_e64 s[0:1], s0, v200
	s_and_b64 s[0:1], vcc, s[0:1]
	s_and_saveexec_b64 s[30:31], s[0:1]
	s_cbranch_execz .LBB0_947
	v_mov_b32_e32 v231, v230
	v_pk_mul_f32 v[76:77], v[78:79], v[230:231]
	v_pk_fma_f32 v[78:79], v[136:137], v[176:177], v[180:181]
	v_pk_fma_f32 v[76:77], v[76:77], v[178:179], v[182:183]
	v_pk_fma_f32 v[80:81], v[128:129], v[164:165], v[168:169]
	v_pk_fma_f32 v[68:69], v[68:69], v[174:175], v[76:77]
	v_pk_fma_f32 v[76:77], v[132:133], v[172:173], v[78:79]
	v_pk_mul_f32 v[78:79], v[82:83], v[230:231]
	v_pk_fma_f32 v[80:81], v[140:141], v[160:161], v[80:81]
	v_pk_fma_f32 v[78:79], v[78:79], v[166:167], v[170:171]
	v_pk_fma_f32 v[80:81], v[92:93], v[152:153], v[80:81]
	v_pk_fma_f32 v[78:79], v[142:143], v[162:163], v[78:79]
	v_mul_f32_e32 v82, 0xbfb8aa3b, v80
	v_pk_fma_f32 v[78:79], v[94:95], v[154:155], v[78:79]
	v_mul_f32_e32 v83, 0xbfb8aa3b, v81
	v_mul_f32_e32 v86, 0xbfb8aa3b, v78
	v_mul_f32_e32 v87, 0xbfb8aa3b, v79
	v_exp_f32_e32 v82, v82
	v_exp_f32_e32 v83, v83
	v_exp_f32_e32 v86, v86
	v_exp_f32_e32 v87, v87
	v_add_f32_e32 v82, 1.0, v82
	v_add_f32_e32 v83, 1.0, v83
	v_add_f32_e32 v86, 1.0, v86
	v_add_f32_e32 v87, 1.0, v87
	v_rcp_f32_e32 v82, v82
	v_rcp_f32_e32 v86, v86
	v_rcp_f32_e32 v87, v87
	v_rcp_f32_e32 v83, v83
	v_pk_fma_f32 v[68:69], v[72:73], v[158:159], v[68:69]
	v_pk_fma_f32 v[72:73], v[84:85], v[156:157], v[76:77]
	v_pk_mul_f32 v[76:77], v[78:79], v[86:87]
	v_pk_mul_f32 v[78:79], v[80:81], v[82:83]
	v_pk_mul_f32 v[68:69], v[68:69], v[76:77]
	v_pk_mul_f32 v[72:73], v[72:73], v[78:79]
	s_nop 0
	v_cvt_pk_bf16_f32 v120, v72, v73
	v_cvt_pk_bf16_f32 v121, v68, v69

; #define LAS __attribute__((address_space(3)))
;     __device__ __forceinline__ void operator()(const f32x4 (&acc)[2][2][4][2], const CU2& u, int wr, int wc, int fr_, int fq_) const {
;     ...
;         for (int n = 0; n < 2; ++n) {
;             const float* wp = cw + 128 * u.pn + cl + 4 * n; const float* bp = cb + 128 * u.pn + cl + 4 * n;
;             const f32x4 g0 = *(const f32x4*)wp, g1 = *(const f32x4*)(wp + 2 * FF_), g2 = *(const f32x4*)(wp + 4 * FF_), gb = *(const f32x4*)bp;
;             const f32x4 v0 = *(const f32x4*)(wp + FF_), v1 = *(const f32x4*)(wp + 3 * FF_), v2 = *(const f32x4*)(wp + 5 * FF_), vb = *(const f32x4*)(bp + FF_);
;             f32x4 pg2 = acc[1][0][2][n] * rsv[6], pg1 = acc[1][0][3][n] * rsv[7], pv2 = acc[1][1][2][n] * rsv[6], pv1 = acc[1][1][3][n] * rsv[7];
; #pragma unroll
;             for (int e = 0; e < 4; ++e) {
;                 pg2[e] = __int_as_float(__builtin_amdgcn_mov_dpp(__float_as_int(pg2[e]), 0x111, 0xF, 0xF, true)); pg1[e] = __int_as_float(__builtin_amdgcn_mov_dpp(__float_as_int(pg1[e]), 0x111, 0xF, 0xF, true));
;                 pv2[e] = __int_as_float(__builtin_amdgcn_mov_dpp(__float_as_int(pv2[e]), 0x111, 0xF, 0xF, true)); pv1[e] = __int_as_float(__builtin_amdgcn_mov_dpp(__float_as_int(pv1[e]), 0x111, 0xF, 0xF, true));
;             }
;             if (fr == 0 && wr == 1) { pg2 = *(const LAS f32x4*)(hal + cl + 4 * n); pg1 = *(const LAS f32x4*)(hal + 256 + cl + 4 * n); pv2 = *(const LAS f32x4*)(hal + 128 + cl + 4 * n); pv1 = *(const LAS f32x4*)(hal + 384 + cl + 4 * n); }
; #pragma unroll
;             for (int j = 0; j < 8; ++j) {
;                 const f32x4 xg = acc[j >> 2][0][j & 3][n] * rsv[j], xv = acc[j >> 2][1][j & 3][n] * rsv[j];
;                 const f32x4 gc = gb + g2 * xg + g1 * pg1 + g0 * pg2, vc = vb + v2 * xv + v1 * pv1 + v0 * pv2;
;                 f32x4 sg;
; #pragma unroll
;                 for (int e = 0; e < 4; ++e) sg[e] = __builtin_amdgcn_rcpf(1.f + __expf(-gc[e]));
;                 const f32x4 o4 = gc * sg * vc;
;                 pg2 = pg1; pg1 = xg; pv2 = pv1; pv1 = xv;
;                 if (rb + j >= 2 && tb + j < T_) { u32x2 w; w.x = cvt_pk_bf16(o4[0], o4[1]); w.y = cvt_pk_bf16(o4[2], o4[3]); *(u32x2*)(act + (size_t)(tb + j) * FF_ + 128 * u.pn + cl + 4 * n) = w; }
.LBB0_949:
	s_or_b64 exec, exec, s[30:31]
	v_mov_b32_e32 v229, v228
	v_mov_b32_e32 v114, v228
	v_mov_b32_e32 v115, v228
	v_pk_mul_f32 v[60:61], v[60:61], v[114:115]
	v_pk_mul_f32 v[58:59], v[58:59], v[228:229]
	v_pk_mul_f32 v[42:43], v[42:43], v[114:115]
	v_pk_mul_f32 v[40:41], v[40:41], v[228:229]
	s_and_saveexec_b64 s[4:5], s[10:11]
	s_cbranch_execz .LBB0_951
	s_waitcnt lgkmcnt(0)
	v_pk_fma_f32 v[114:115], v[42:43], v[102:103], v[106:107]
	v_pk_fma_f32 v[116:117], v[40:41], v[100:101], v[104:105]
	s_waitcnt lgkmcnt(0)
	v_pk_fma_f32 v[114:115], v[98:99], v[56:57], v[114:115]
	v_pk_fma_f32 v[116:117], v[96:97], v[54:55], v[116:117]
	v_pk_fma_f32 v[74:75], v[82:83], v[74:75], v[114:115]
	v_pk_fma_f32 v[72:73], v[80:81], v[72:73], v[116:117]
	v_pk_fma_f32 v[114:115], v[60:61], v[90:91], v[94:95]
	v_pk_fma_f32 v[116:117], v[58:59], v[88:89], v[92:93]
	v_pk_fma_f32 v[114:115], v[86:87], v[46:47], v[114:115]
	v_pk_fma_f32 v[116:117], v[84:85], v[44:45], v[116:117]
	v_pk_fma_f32 v[70:71], v[78:79], v[70:71], v[114:115]
	v_pk_fma_f32 v[68:69], v[76:77], v[68:69], v[116:117]
	v_mul_f32_e32 v116, 0xbfb8aa3b, v70
	v_mul_f32_e32 v114, 0xbfb8aa3b, v68
	v_mul_f32_e32 v115, 0xbfb8aa3b, v69
	v_mul_f32_e32 v117, 0xbfb8aa3b, v71
	v_exp_f32_e32 v114, v114
	v_exp_f32_e32 v115, v115
	v_exp_f32_e32 v116, v116
	v_exp_f32_e32 v117, v117
	v_add_f32_e32 v114, 1.0, v114
	v_add_f32_e32 v115, 1.0, v115
	v_add_f32_e32 v116, 1.0, v116
	v_add_f32_e32 v117, 1.0, v117
	v_rcp_f32_e32 v114, v114
	v_rcp_f32_e32 v115, v115
	v_rcp_f32_e32 v116, v116
	v_rcp_f32_e32 v117, v117
	v_pk_mul_f32 v[68:69], v[68:69], v[114:115]
	s_nop 0
	v_pk_mul_f32 v[68:69], v[72:73], v[68:69]
	v_pk_mul_f32 v[70:71], v[70:71], v[116:117]
	v_cvt_pk_bf16_f32 v150, v68, v69
	s_nop 0
	v_pk_mul_f32 v[70:71], v[74:75], v[70:71]
	s_nop 0
	v_cvt_pk_bf16_f32 v151, v70, v71
	v_mad_i64_i32 v[70:71], s[10:11], v200, s37, v[50:51]
	global_store_dwordx4 v[70:71], v[148:151], off
.LBB0_951:
	s_or_b64 exec, exec, s[4:5]
	v_mov_b32_e32 v225, v224
	s_waitcnt lgkmcnt(0)
	v_mov_b32_e32 v68, v224
	v_mov_b32_e32 v69, v224
	v_pk_mul_f32 v[38:39], v[38:39], v[68:69]
	v_pk_mul_f32 v[36:37], v[36:37], v[224:225]
	v_pk_mul_f32 v[34:35], v[34:35], v[68:69]
	v_pk_mul_f32 v[32:33], v[32:33], v[224:225]
	s_and_saveexec_b64 s[4:5], s[6:7]
	s_cbranch_execz .LBB0_953
	v_pk_fma_f32 v[68:69], v[34:35], v[102:103], v[106:107]
	v_pk_fma_f32 v[70:71], v[32:33], v[100:101], v[104:105]
	v_pk_fma_f32 v[68:69], v[42:43], v[98:99], v[68:69]
	v_pk_fma_f32 v[70:71], v[40:41], v[96:97], v[70:71]
	v_pk_fma_f32 v[56:57], v[82:83], v[56:57], v[68:69]
	v_pk_fma_f32 v[54:55], v[80:81], v[54:55], v[70:71]
	v_pk_fma_f32 v[68:69], v[38:39], v[90:91], v[94:95]
	v_pk_fma_f32 v[70:71], v[36:37], v[88:89], v[92:93]
	v_pk_fma_f32 v[68:69], v[60:61], v[86:87], v[68:69]
	v_pk_fma_f32 v[70:71], v[58:59], v[84:85], v[70:71]
	v_pk_fma_f32 v[46:47], v[78:79], v[46:47], v[68:69]
	v_pk_fma_f32 v[44:45], v[76:77], v[44:45], v[70:71]
	v_mul_f32_e32 v70, 0xbfb8aa3b, v46
	v_mul_f32_e32 v68, 0xbfb8aa3b, v44
	v_mul_f32_e32 v69, 0xbfb8aa3b, v45
	v_mul_f32_e32 v71, 0xbfb8aa3b, v47
	v_exp_f32_e32 v68, v68
	v_exp_f32_e32 v69, v69
	v_exp_f32_e32 v70, v70
	v_exp_f32_e32 v71, v71
	v_add_f32_e32 v68, 1.0, v68
	v_add_f32_e32 v69, 1.0, v69
	v_add_f32_e32 v70, 1.0, v70
	v_add_f32_e32 v71, 1.0, v71
	v_rcp_f32_e32 v68, v68
	v_rcp_f32_e32 v69, v69
	v_rcp_f32_e32 v70, v70
	v_rcp_f32_e32 v71, v71
	v_pk_mul_f32 v[44:45], v[44:45], v[68:69]
	s_nop 0
	v_pk_mul_f32 v[44:45], v[54:55], v[44:45]
	v_pk_mul_f32 v[46:47], v[46:47], v[70:71]
	v_cvt_pk_bf16_f32 v146, v44, v45
	s_nop 0
	v_pk_mul_f32 v[46:47], v[56:57], v[46:47]
	s_nop 0
	v_cvt_pk_bf16_f32 v147, v46, v47
	v_mad_i64_i32 v[46:47], s[6:7], v223, s37, v[50:51]
	global_store_dwordx4 v[46:47], v[144:147], off
.LBB0_953:
	s_or_b64 exec, exec, s[4:5]
	v_mov_b32_e32 v223, v222
	v_mov_b32_e32 v44, v222
	v_mov_b32_e32 v45, v222
	v_pk_mul_f32 v[30:31], v[30:31], v[44:45]
	v_pk_mul_f32 v[28:29], v[28:29], v[222:223]
	v_pk_mul_f32 v[26:27], v[26:27], v[44:45]
	v_pk_mul_f32 v[24:25], v[24:25], v[222:223]
	s_and_saveexec_b64 s[4:5], s[8:9]
	s_cbranch_execz .LBB0_955
	v_pk_fma_f32 v[44:45], v[26:27], v[102:103], v[106:107]
	v_pk_fma_f32 v[46:47], v[24:25], v[100:101], v[104:105]
	v_pk_fma_f32 v[44:45], v[34:35], v[98:99], v[44:45]
	v_pk_fma_f32 v[46:47], v[32:33], v[96:97], v[46:47]
	v_pk_fma_f32 v[42:43], v[42:43], v[82:83], v[44:45]
	v_pk_fma_f32 v[40:41], v[40:41], v[80:81], v[46:47]
	v_pk_fma_f32 v[44:45], v[30:31], v[90:91], v[94:95]
	v_pk_fma_f32 v[46:47], v[28:29], v[88:89], v[92:93]
	v_pk_fma_f32 v[44:45], v[38:39], v[86:87], v[44:45]
	v_pk_fma_f32 v[46:47], v[36:37], v[84:85], v[46:47]
	v_pk_fma_f32 v[44:45], v[60:61], v[78:79], v[44:45]
	v_pk_fma_f32 v[46:47], v[58:59], v[76:77], v[46:47]
	v_mul_f32_e32 v56, 0xbfb8aa3b, v44
	v_mul_f32_e32 v54, 0xbfb8aa3b, v46
	v_mul_f32_e32 v55, 0xbfb8aa3b, v47
	v_mul_f32_e32 v57, 0xbfb8aa3b, v45
	v_exp_f32_e32 v54, v54
	v_exp_f32_e32 v55, v55
	v_exp_f32_e32 v56, v56
	v_exp_f32_e32 v57, v57
	v_add_f32_e32 v54, 1.0, v54
	v_add_f32_e32 v55, 1.0, v55
	v_add_f32_e32 v56, 1.0, v56
	v_add_f32_e32 v57, 1.0, v57
	v_rcp_f32_e32 v54, v54
	v_rcp_f32_e32 v55, v55
	v_rcp_f32_e32 v56, v56
	v_rcp_f32_e32 v57, v57
	v_pk_mul_f32 v[46:47], v[46:47], v[54:55]
	s_nop 0
	v_pk_mul_f32 v[40:41], v[40:41], v[46:47]
	v_pk_mul_f32 v[44:45], v[44:45], v[56:57]
	v_cvt_pk_bf16_f32 v186, v40, v41
	s_nop 0
	v_pk_mul_f32 v[42:43], v[42:43], v[44:45]
	s_nop 0
	v_cvt_pk_bf16_f32 v187, v42, v43
	v_mad_i64_i32 v[42:43], s[6:7], v221, s37, v[50:51]
	global_store_dwordx4 v[42:43], v[184:187], off
; __device__ __forceinline__ unsigned cvt_pk_bf16(float lo, float hi) { unsigned r; asm("v_cvt_pk_bf16_f32 %0, %1, %2" : "=v"(r) : "v"(lo), "v"(hi)); return r; }
;     __device__ __forceinline__ void operator()(const f32x4 (&acc)[2][2][4][2], const CU2& u, int wr, int wc, int fr_, int fq_) const {
;     ...
;             for (int j = 0; j < 8; ++j) {
;                 const f32x4 xg = acc[j >> 2][0][j & 3][n] * rsv[j], xv = acc[j >> 2][1][j & 3][n] * rsv[j];
;                 const f32x4 gc = gb + g2 * xg + g1 * pg1 + g0 * pg2, vc = vb + v2 * xv + v1 * pv1 + v0 * pv2;
;                 f32x4 sg;
; #pragma unroll
;                 for (int e = 0; e < 4; ++e) sg[e] = __builtin_amdgcn_rcpf(1.f + __expf(-gc[e]));
;                 const f32x4 o4 = gc * sg * vc;
;                 pg2 = pg1; pg1 = xg; pv2 = pv1; pv1 = xv;
;                 if (rb + j >= 2 && tb + j < T_) { u32x2 w; w.x = cvt_pk_bf16(o4[0], o4[1]); w.y = cvt_pk_bf16(o4[2], o4[3]); *(u32x2*)(act + (size_t)(tb + j) * FF_ + 128 * u.pn + cl + 4 * n) = w; }
.LBB0_955:
	s_or_b64 exec, exec, s[4:5]
	v_mov_b32_e32 v221, v220
	v_mov_b32_e32 v40, v220
	v_mov_b32_e32 v41, v220
	v_pk_mul_f32 v[22:23], v[22:23], v[40:41]
	v_pk_mul_f32 v[20:21], v[20:21], v[220:221]
	v_pk_mul_f32 v[18:19], v[18:19], v[40:41]
	v_pk_mul_f32 v[16:17], v[16:17], v[220:221]
	s_and_saveexec_b64 s[4:5], s[12:13]
	s_cbranch_execz .LBB0_957
	v_pk_fma_f32 v[40:41], v[18:19], v[102:103], v[106:107]
	v_pk_fma_f32 v[42:43], v[16:17], v[100:101], v[104:105]
	v_pk_fma_f32 v[40:41], v[26:27], v[98:99], v[40:41]
	v_pk_fma_f32 v[42:43], v[24:25], v[96:97], v[42:43]
	v_pk_fma_f32 v[34:35], v[34:35], v[82:83], v[40:41]
	v_pk_fma_f32 v[32:33], v[32:33], v[80:81], v[42:43]
	v_pk_fma_f32 v[40:41], v[22:23], v[90:91], v[94:95]
	v_pk_fma_f32 v[42:43], v[20:21], v[88:89], v[92:93]
	v_pk_fma_f32 v[40:41], v[30:31], v[86:87], v[40:41]
	v_pk_fma_f32 v[42:43], v[28:29], v[84:85], v[42:43]
	v_pk_fma_f32 v[38:39], v[38:39], v[78:79], v[40:41]
	v_pk_fma_f32 v[36:37], v[36:37], v[76:77], v[42:43]
	v_mul_f32_e32 v42, 0xbfb8aa3b, v38
	v_mul_f32_e32 v40, 0xbfb8aa3b, v36
	v_mul_f32_e32 v41, 0xbfb8aa3b, v37
	v_mul_f32_e32 v43, 0xbfb8aa3b, v39
	v_exp_f32_e32 v40, v40
	v_exp_f32_e32 v41, v41
	v_exp_f32_e32 v42, v42
	v_exp_f32_e32 v43, v43
	v_add_f32_e32 v40, 1.0, v40
	v_add_f32_e32 v41, 1.0, v41
	v_add_f32_e32 v42, 1.0, v42
	v_add_f32_e32 v43, 1.0, v43
	v_rcp_f32_e32 v40, v40
	v_rcp_f32_e32 v41, v41
	v_rcp_f32_e32 v42, v42
	v_rcp_f32_e32 v43, v43
	v_pk_mul_f32 v[36:37], v[36:37], v[40:41]
	s_nop 0
	v_pk_mul_f32 v[32:33], v[32:33], v[36:37]
	v_pk_mul_f32 v[38:39], v[38:39], v[42:43]
	v_cvt_pk_bf16_f32 v190, v32, v33
	s_nop 0
	v_pk_mul_f32 v[34:35], v[34:35], v[38:39]
	s_nop 0
	v_cvt_pk_bf16_f32 v191, v34, v35
	v_mad_i64_i32 v[34:35], s[6:7], v219, s37, v[50:51]
	global_store_dwordx4 v[34:35], v[188:191], off
.LBB0_957:
	s_or_b64 exec, exec, s[4:5]
	v_mov_b32_e32 v219, v218
	v_mov_b32_e32 v32, v218
	v_mov_b32_e32 v33, v218
	v_pk_mul_f32 v[14:15], v[14:15], v[32:33]
	v_pk_mul_f32 v[12:13], v[12:13], v[218:219]
	v_pk_mul_f32 v[10:11], v[10:11], v[32:33]
	v_pk_mul_f32 v[8:9], v[8:9], v[218:219]
	s_and_saveexec_b64 s[4:5], s[14:15]
	s_cbranch_execz .LBB0_959
	v_pk_fma_f32 v[32:33], v[10:11], v[102:103], v[106:107]
	v_pk_fma_f32 v[34:35], v[8:9], v[100:101], v[104:105]
	v_pk_fma_f32 v[32:33], v[18:19], v[98:99], v[32:33]
	v_pk_fma_f32 v[34:35], v[16:17], v[96:97], v[34:35]
	v_pk_fma_f32 v[26:27], v[26:27], v[82:83], v[32:33]
	v_pk_fma_f32 v[24:25], v[24:25], v[80:81], v[34:35]
	v_pk_fma_f32 v[32:33], v[14:15], v[90:91], v[94:95]
	v_pk_fma_f32 v[34:35], v[12:13], v[88:89], v[92:93]
	v_pk_fma_f32 v[32:33], v[22:23], v[86:87], v[32:33]
	v_pk_fma_f32 v[34:35], v[20:21], v[84:85], v[34:35]
	v_pk_fma_f32 v[30:31], v[30:31], v[78:79], v[32:33]
	v_pk_fma_f32 v[28:29], v[28:29], v[76:77], v[34:35]
	v_mul_f32_e32 v34, 0xbfb8aa3b, v30
	v_mul_f32_e32 v32, 0xbfb8aa3b, v28
	v_mul_f32_e32 v33, 0xbfb8aa3b, v29
	v_mul_f32_e32 v35, 0xbfb8aa3b, v31
	v_exp_f32_e32 v32, v32
	v_exp_f32_e32 v33, v33
	v_exp_f32_e32 v34, v34
	v_exp_f32_e32 v35, v35
	v_add_f32_e32 v32, 1.0, v32
	v_add_f32_e32 v33, 1.0, v33
	v_add_f32_e32 v34, 1.0, v34
	v_add_f32_e32 v35, 1.0, v35
	v_rcp_f32_e32 v32, v32
	v_rcp_f32_e32 v33, v33
	v_rcp_f32_e32 v34, v34
	v_rcp_f32_e32 v35, v35
	v_pk_mul_f32 v[28:29], v[28:29], v[32:33]
	s_nop 0
	v_pk_mul_f32 v[24:25], v[24:25], v[28:29]
	v_pk_mul_f32 v[30:31], v[30:31], v[34:35]
	v_cvt_pk_bf16_f32 v194, v24, v25
	s_nop 0
	v_pk_mul_f32 v[26:27], v[26:27], v[30:31]
	s_nop 0
	v_cvt_pk_bf16_f32 v195, v26, v27
	v_mad_i64_i32 v[26:27], s[6:7], v217, s37, v[50:51]
	global_store_dwordx4 v[26:27], v[192:195], off
; __device__ __forceinline__ unsigned cvt_pk_bf16(float lo, float hi) { unsigned r; asm("v_cvt_pk_bf16_f32 %0, %1, %2" : "=v"(r) : "v"(lo), "v"(hi)); return r; }
;     __device__ __forceinline__ void operator()(const f32x4 (&acc)[2][2][4][2], const CU2& u, int wr, int wc, int fr_, int fq_) const {
;     ...
;             for (int j = 0; j < 8; ++j) {
;                 const f32x4 xg = acc[j >> 2][0][j & 3][n] * rsv[j], xv = acc[j >> 2][1][j & 3][n] * rsv[j];
;                 const f32x4 gc = gb + g2 * xg + g1 * pg1 + g0 * pg2, vc = vb + v2 * xv + v1 * pv1 + v0 * pv2;
;                 f32x4 sg;
; #pragma unroll
;                 for (int e = 0; e < 4; ++e) sg[e] = __builtin_amdgcn_rcpf(1.f + __expf(-gc[e]));
;                 const f32x4 o4 = gc * sg * vc;
;                 pg2 = pg1; pg1 = xg; pv2 = pv1; pv1 = xv;
;                 if (rb + j >= 2 && tb + j < T_) { u32x2 w; w.x = cvt_pk_bf16(o4[0], o4[1]); w.y = cvt_pk_bf16(o4[2], o4[3]); *(u32x2*)(act + (size_t)(tb + j) * FF_ + 128 * u.pn + cl + 4 * n) = w; }
.LBB0_959:
	s_or_b64 exec, exec, s[4:5]
	v_mov_b32_e32 v217, v216
	v_mov_b32_e32 v24, v216
	v_mov_b32_e32 v25, v216
	v_pk_mul_f32 v[6:7], v[6:7], v[24:25]
	v_pk_mul_f32 v[4:5], v[4:5], v[216:217]
	v_pk_mul_f32 v[2:3], v[2:3], v[24:25]
	v_pk_mul_f32 v[0:1], v[0:1], v[216:217]
	s_and_saveexec_b64 s[4:5], s[26:27]
	s_cbranch_execz .LBB0_961
	v_pk_fma_f32 v[24:25], v[2:3], v[102:103], v[106:107]
	v_pk_fma_f32 v[26:27], v[0:1], v[100:101], v[104:105]
	v_pk_fma_f32 v[24:25], v[10:11], v[98:99], v[24:25]
	v_pk_fma_f32 v[26:27], v[8:9], v[96:97], v[26:27]
	v_pk_fma_f32 v[18:19], v[18:19], v[82:83], v[24:25]
	v_pk_fma_f32 v[16:17], v[16:17], v[80:81], v[26:27]
	v_pk_fma_f32 v[24:25], v[6:7], v[90:91], v[94:95]
	v_pk_fma_f32 v[26:27], v[4:5], v[88:89], v[92:93]
	v_pk_fma_f32 v[24:25], v[14:15], v[86:87], v[24:25]
	v_pk_fma_f32 v[26:27], v[12:13], v[84:85], v[26:27]
	v_pk_fma_f32 v[22:23], v[22:23], v[78:79], v[24:25]
	v_pk_fma_f32 v[20:21], v[20:21], v[76:77], v[26:27]
	v_mul_f32_e32 v26, 0xbfb8aa3b, v22
	v_mul_f32_e32 v24, 0xbfb8aa3b, v20
	v_mul_f32_e32 v25, 0xbfb8aa3b, v21
	v_mul_f32_e32 v27, 0xbfb8aa3b, v23
	v_exp_f32_e32 v24, v24
	v_exp_f32_e32 v25, v25
	v_exp_f32_e32 v26, v26
	v_exp_f32_e32 v27, v27
	v_add_f32_e32 v24, 1.0, v24
	v_add_f32_e32 v25, 1.0, v25
	v_add_f32_e32 v26, 1.0, v26
	v_add_f32_e32 v27, 1.0, v27
	v_rcp_f32_e32 v24, v24
	v_rcp_f32_e32 v25, v25
	v_rcp_f32_e32 v26, v26
	v_rcp_f32_e32 v27, v27
	v_pk_mul_f32 v[20:21], v[20:21], v[24:25]
	s_nop 0
	v_pk_mul_f32 v[16:17], v[16:17], v[20:21]
	v_pk_mul_f32 v[22:23], v[22:23], v[26:27]
	v_cvt_pk_bf16_f32 v198, v16, v17
	s_nop 0
	v_pk_mul_f32 v[18:19], v[18:19], v[22:23]
	s_nop 0
	v_cvt_pk_bf16_f32 v199, v18, v19
	v_mad_i64_i32 v[18:19], s[6:7], v246, s37, v[50:51]
	global_store_dwordx4 v[18:19], v[196:199], off
.LBB0_961:
	s_or_b64 exec, exec, s[4:5]
	s_and_saveexec_b64 s[4:5], s[28:29]
	s_cbranch_execz .LBB0_963
	v_pk_fma_f32 v[16:17], v[110:111], v[102:103], v[106:107]
	v_pk_fma_f32 v[18:19], v[62:63], v[100:101], v[104:105]
	v_pk_fma_f32 v[16:17], v[2:3], v[98:99], v[16:17]
	v_pk_fma_f32 v[18:19], v[0:1], v[96:97], v[18:19]
	v_pk_fma_f32 v[10:11], v[10:11], v[82:83], v[16:17]
	v_pk_fma_f32 v[8:9], v[8:9], v[80:81], v[18:19]
	v_pk_fma_f32 v[16:17], v[64:65], v[90:91], v[94:95]
	v_pk_fma_f32 v[18:19], v[48:49], v[88:89], v[92:93]
	v_pk_fma_f32 v[16:17], v[6:7], v[86:87], v[16:17]
	v_pk_fma_f32 v[18:19], v[4:5], v[84:85], v[18:19]
	v_pk_fma_f32 v[14:15], v[14:15], v[78:79], v[16:17]
	v_pk_fma_f32 v[12:13], v[12:13], v[76:77], v[18:19]
	v_mul_f32_e32 v18, 0xbfb8aa3b, v14
	v_mul_f32_e32 v16, 0xbfb8aa3b, v12
	v_mul_f32_e32 v17, 0xbfb8aa3b, v13
	v_mul_f32_e32 v19, 0xbfb8aa3b, v15
	v_exp_f32_e32 v16, v16
	v_exp_f32_e32 v17, v17
	v_exp_f32_e32 v18, v18
	v_exp_f32_e32 v19, v19
	v_add_f32_e32 v16, 1.0, v16
	v_add_f32_e32 v17, 1.0, v17
	v_add_f32_e32 v18, 1.0, v18
	v_add_f32_e32 v19, 1.0, v19
	v_rcp_f32_e32 v16, v16
	v_rcp_f32_e32 v17, v17
	v_rcp_f32_e32 v18, v18
	v_rcp_f32_e32 v19, v19
	v_pk_mul_f32 v[12:13], v[12:13], v[16:17]
	s_nop 0
	v_pk_mul_f32 v[8:9], v[8:9], v[12:13]
	v_pk_mul_f32 v[14:15], v[14:15], v[18:19]
	v_cvt_pk_bf16_f32 v250, v8, v9
	s_nop 0
	v_pk_mul_f32 v[10:11], v[10:11], v[14:15]
	s_nop 0
	v_cvt_pk_bf16_f32 v251, v10, v11
	v_mad_i64_i32 v[10:11], s[6:7], v245, s37, v[50:51]
	global_store_dwordx4 v[10:11], v[248:251], off
.LBB0_963:
	s_or_b64 exec, exec, s[4:5]
	s_and_saveexec_b64 s[4:5], s[0:1]
	s_cbranch_execz .LBB0_965
	v_pk_fma_f32 v[12:13], v[52:53], v[88:89], v[92:93]
	v_pk_fma_f32 v[8:9], v[112:113], v[102:103], v[106:107]
	v_pk_fma_f32 v[12:13], v[48:49], v[84:85], v[12:13]
	v_pk_fma_f32 v[10:11], v[66:67], v[100:101], v[104:105]
	v_pk_fma_f32 v[4:5], v[4:5], v[76:77], v[12:13]
	v_pk_fma_f32 v[8:9], v[110:111], v[98:99], v[8:9]
	v_mul_f32_e32 v12, 0xbfb8aa3b, v4
	v_exp_f32_e32 v14, v12
	v_pk_fma_f32 v[12:13], v[108:109], v[90:91], v[94:95]
	v_pk_fma_f32 v[10:11], v[62:63], v[96:97], v[10:11]
	v_pk_fma_f32 v[12:13], v[64:65], v[86:87], v[12:13]
	v_pk_fma_f32 v[2:3], v[2:3], v[82:83], v[8:9]
	v_pk_fma_f32 v[6:7], v[6:7], v[78:79], v[12:13]
	v_add_f32_e32 v12, 1.0, v14
	v_mul_f32_e32 v13, 0xbfb8aa3b, v5
	v_mul_f32_e32 v14, 0xbfb8aa3b, v6
	v_mul_f32_e32 v15, 0xbfb8aa3b, v7
	v_exp_f32_e32 v13, v13
	v_exp_f32_e32 v14, v14
	v_exp_f32_e32 v15, v15
	v_rcp_f32_e32 v12, v12
	v_add_f32_e32 v13, 1.0, v13
	v_add_f32_e32 v14, 1.0, v14
	v_add_f32_e32 v15, 1.0, v15
	v_rcp_f32_e32 v14, v14
	v_rcp_f32_e32 v15, v15
	v_rcp_f32_e32 v13, v13
	v_pk_fma_f32 v[0:1], v[0:1], v[80:81], v[10:11]
	v_pk_mul_f32 v[6:7], v[6:7], v[14:15]
	v_pk_mul_f32 v[4:5], v[4:5], v[12:13]
	v_pk_mul_f32 v[2:3], v[2:3], v[6:7]
	v_pk_mul_f32 v[0:1], v[0:1], v[4:5]
	s_nop 0
	v_cvt_pk_bf16_f32 v122, v0, v1
	v_cvt_pk_bf16_f32 v123, v2, v3
	v_mad_i64_i32 v[2:3], s[0:1], v244, s37, v[50:51]
	global_store_dwordx4 v[2:3], v[120:123], off
